# lever 7: the no-op 0+x v_add_f32 at the head of both attention row-sum chains removed (on top of v12)
# baseline (speedup 1.0000x reference)
; __device__ __forceinline__ unsigned pk2(float lo, float hi) { return pg8::cvt_pk_bf16(lo, hi); }
; #define FA_MFMA(a, b, c) __builtin_amdgcn_mfma_f32_32x32x16_bf16((a), (b), (c), 0, 0, 0)
; template <int DQK, bool HAS_LSE>
; __device__ __forceinline__ void unit(LAS unsigned char* lds, const Desc& d) {
;     ...
;             float ls = 0.f;
; #pragma unroll
;             for (int i = 0; i < 16; ++i) { p0[i] = __builtin_amdgcn_exp2f(p0[i] - mn); p1[i] = __builtin_amdgcn_exp2f(p1[i] - mn); ls += p0[i] + p1[i]; }
;             l = l * corr + ls;
;             if (grew) {
; #pragma unroll
;                 for (int db = 0; db < 4; ++db)
; #pragma unroll
;                     for (int i = 0; i < 16; ++i) o[db][i] *= corr;
;             }
; #pragma unroll
;             for (int g4 = 0; g4 < 4; ++g4) {
;                 v4u pkw;
;                 if (g4 == 0) { pkw.x = pk2(p0[0], p0[1]); pkw.y = pk2(p0[2], p0[3]); pkw.z = pk2(p0[4], p0[5]); pkw.w = pk2(p0[6], p0[7]); }
;                 if (g4 == 1) { pkw.x = pk2(p0[8], p0[9]); pkw.y = pk2(p0[10], p0[11]); pkw.z = pk2(p0[12], p0[13]); pkw.w = pk2(p0[14], p0[15]); }
;                 if (g4 == 2) { pkw.x = pk2(p1[0], p1[1]); pkw.y = pk2(p1[2], p1[3]); pkw.z = pk2(p1[4], p1[5]); pkw.w = pk2(p1[6], p1[7]); }
;                 if (g4 == 3) { pkw.x = pk2(p1[8], p1[9]); pkw.y = pk2(p1[10], p1[11]); pkw.z = pk2(p1[12], p1[13]); pkw.w = pk2(p1[14], p1[15]); }
;                 const bf16x8 pf = __builtin_bit_cast(bf16x8, pkw);
;                 vtr8_wait(vlo[g4 & 1], vhh[g4 & 1]);
;                 if (g4 == 0) vtr8_issue<4096>(vba, vlo[1], vhh[1]);
;                 if (g4 == 1) vtr8_issue<8192>(vba, vlo[0], vhh[0]);
;                 if (g4 == 2) vtr8_issue<12288>(vba, vlo[1], vhh[1]);
; #pragma unroll
;                 for (int db = 0; db < 4; ++db) {
;                     const bf16x8 vf = __builtin_shufflevector(vlo[g4 & 1][db], vhh[g4 & 1][db], 0, 1, 2, 3, 4, 5, 6, 7);
;                     o[db] = FA_MFMA(vf, pf, o[db]);
;                 }
;             }
.LBB0_522:
	v_sub_f32_e32 v67, v84, v153
	v_sub_f32_e32 v68, v68, v153
	v_exp_f32_e32 v67, v67
	v_exp_f32_e32 v84, v68
	v_sub_f32_e32 v85, v85, v153
	v_sub_f32_e32 v69, v69, v153
	v_exp_f32_e32 v178, v85
	v_exp_f32_e32 v85, v69
	v_add_f32_e32 v68, v67, v84
	v_sub_f32_e32 v70, v70, v153
	v_add_f32_e32 v69, v178, v85
	v_add_f32_e32 v68, v69, v68
	v_sub_f32_e32 v69, v86, v153
	v_exp_f32_e32 v69, v69
	v_exp_f32_e32 v86, v70
	s_nop 0
	v_add_f32_e32 v70, v69, v86
	v_add_f32_e32 v68, v70, v68
	v_sub_f32_e32 v70, v87, v153
	v_exp_f32_e32 v179, v70
	v_sub_f32_e32 v70, v71, v153
	v_exp_f32_e32 v87, v70
	s_nop 0
	v_add_f32_e32 v70, v179, v87
	v_add_f32_e32 v68, v70, v68
	v_sub_f32_e32 v70, v88, v153
	v_exp_f32_e32 v180, v70
	v_sub_f32_e32 v70, v72, v153
	v_exp_f32_e32 v88, v70
	s_nop 0
	v_add_f32_e32 v70, v180, v88
	v_add_f32_e32 v68, v70, v68
	v_sub_f32_e32 v70, v89, v153
	v_exp_f32_e32 v72, v70
	v_sub_f32_e32 v70, v73, v153
	v_exp_f32_e32 v89, v70
	s_nop 0
	v_add_f32_e32 v70, v72, v89
	v_add_f32_e32 v68, v70, v68
	v_sub_f32_e32 v70, v90, v153
	v_exp_f32_e32 v73, v70
	v_sub_f32_e32 v70, v74, v153
	v_exp_f32_e32 v90, v70
	s_nop 0
	v_add_f32_e32 v70, v73, v90
	v_add_f32_e32 v68, v70, v68
	v_sub_f32_e32 v70, v91, v153
	v_exp_f32_e32 v181, v70
	v_sub_f32_e32 v70, v75, v153
	v_exp_f32_e32 v91, v70
	s_nop 0
	v_add_f32_e32 v70, v181, v91
	v_add_f32_e32 v68, v70, v68
	v_sub_f32_e32 v70, v92, v153
	v_exp_f32_e32 v182, v70
	v_sub_f32_e32 v70, v76, v153
	v_exp_f32_e32 v75, v70
	s_nop 0
	v_add_f32_e32 v70, v182, v75
	v_add_f32_e32 v68, v70, v68
	v_sub_f32_e32 v70, v93, v153
	v_exp_f32_e32 v183, v70
	v_sub_f32_e32 v70, v77, v153
	v_exp_f32_e32 v76, v70
	s_nop 0
	v_add_f32_e32 v70, v183, v76
	v_add_f32_e32 v68, v70, v68
	v_sub_f32_e32 v70, v94, v153
	v_exp_f32_e32 v184, v70
	v_sub_f32_e32 v70, v78, v153
	v_exp_f32_e32 v77, v70
	s_nop 0
	v_add_f32_e32 v70, v184, v77
	v_add_f32_e32 v68, v70, v68
	v_sub_f32_e32 v70, v95, v153
	v_exp_f32_e32 v185, v70
	v_sub_f32_e32 v70, v79, v153
	v_exp_f32_e32 v78, v70
	s_nop 0
	v_add_f32_e32 v70, v185, v78
	v_add_f32_e32 v68, v70, v68
	v_sub_f32_e32 v70, v96, v153
	v_exp_f32_e32 v186, v70
	v_sub_f32_e32 v70, v80, v153
	v_exp_f32_e32 v79, v70
	s_nop 0
	v_add_f32_e32 v70, v186, v79
	v_add_f32_e32 v68, v70, v68
	v_sub_f32_e32 v70, v97, v153
	v_exp_f32_e32 v187, v70
	v_sub_f32_e32 v70, v81, v153
	v_exp_f32_e32 v80, v70
	s_nop 0
	v_add_f32_e32 v70, v187, v80
	v_add_f32_e32 v68, v70, v68
	v_sub_f32_e32 v70, v98, v153
	v_exp_f32_e32 v188, v70
	v_sub_f32_e32 v70, v82, v153
	v_exp_f32_e32 v81, v70
	s_nop 0
	v_add_f32_e32 v70, v188, v81
	v_add_f32_e32 v68, v70, v68
	v_sub_f32_e32 v70, v99, v153
	v_exp_f32_e32 v189, v70
	v_sub_f32_e32 v70, v83, v153
	v_exp_f32_e32 v82, v70
	s_nop 0
	v_add_f32_e32 v70, v189, v82
	v_add_f32_e32 v74, v70, v68
	v_cvt_pk_bf16_f32 v70, v67, v178
	v_cvt_pk_bf16_f32 v71, v69, v179
	v_cvt_pk_bf16_f32 v72, v180, v72
	v_cvt_pk_bf16_f32 v73, v73, v181
	s_waitcnt lgkmcnt(0)
	v_fmac_f32_e32 v74, v66, v154
	v_mfma_f32_32x32x16_bf16 v[50:65], v[144:147], v[70:73], v[50:65]
	ds_read_b64_tr_b16 v[178:179], v177 offset:4096
	ds_read_b64_tr_b16 v[180:181], v177 offset:6144
	ds_read_b64_tr_b16 v[96:97], v177 offset:4608
	ds_read_b64_tr_b16 v[98:99], v177 offset:6656
	ds_read_b64_tr_b16 v[92:93], v177 offset:5120
	ds_read_b64_tr_b16 v[94:95], v177 offset:7168
	ds_read_b64_tr_b16 v[66:67], v177 offset:5632
	ds_read_b64_tr_b16 v[68:69], v177 offset:7680
	v_mfma_f32_32x32x16_bf16 v[34:49], v[140:143], v[70:73], v[34:49]
	v_mfma_f32_32x32x16_bf16 v[18:33], v[136:139], v[70:73], v[18:33]
	v_mfma_f32_32x32x16_bf16 v[2:17], v[132:135], v[70:73], v[2:17]
	v_cvt_pk_bf16_f32 v132, v182, v183
	v_cvt_pk_bf16_f32 v133, v184, v185
	v_cvt_pk_bf16_f32 v134, v186, v187
	v_cvt_pk_bf16_f32 v135, v188, v189
	s_waitcnt lgkmcnt(0)
	ds_read_b64_tr_b16 v[144:145], v177 offset:8192
	ds_read_b64_tr_b16 v[146:147], v177 offset:10240
	ds_read_b64_tr_b16 v[140:141], v177 offset:8704
	ds_read_b64_tr_b16 v[142:143], v177 offset:10752
	ds_read_b64_tr_b16 v[136:137], v177 offset:9216
	ds_read_b64_tr_b16 v[138:139], v177 offset:11264
	ds_read_b64_tr_b16 v[70:71], v177 offset:9728
	ds_read_b64_tr_b16 v[72:73], v177 offset:11776
	s_nop 0
	v_mfma_f32_32x32x16_bf16 v[50:65], v[178:181], v[132:135], v[50:65]
	v_mfma_f32_32x32x16_bf16 v[34:49], v[96:99], v[132:135], v[34:49]
	v_mfma_f32_32x32x16_bf16 v[18:33], v[92:95], v[132:135], v[18:33]
	v_mfma_f32_32x32x16_bf16 v[2:17], v[66:69], v[132:135], v[2:17]
	v_cvt_pk_bf16_f32 v66, v84, v85
	v_cvt_pk_bf16_f32 v67, v86, v87
	v_cvt_pk_bf16_f32 v68, v88, v89
	v_cvt_pk_bf16_f32 v69, v90, v91
	s_waitcnt lgkmcnt(0)
	ds_read_b64_tr_b16 v[96:97], v177 offset:12288
	ds_read_b64_tr_b16 v[98:99], v177 offset:14336
	ds_read_b64_tr_b16 v[92:93], v177 offset:12800
	ds_read_b64_tr_b16 v[94:95], v177 offset:14848
	ds_read_b64_tr_b16 v[88:89], v177 offset:13312
	ds_read_b64_tr_b16 v[90:91], v177 offset:15360
	ds_read_b64_tr_b16 v[84:85], v177 offset:13824
	ds_read_b64_tr_b16 v[86:87], v177 offset:15872
	s_nop 0
	v_mfma_f32_32x32x16_bf16 v[50:65], v[144:147], v[66:69], v[50:65]
	v_mfma_f32_32x32x16_bf16 v[34:49], v[140:143], v[66:69], v[34:49]
	v_mfma_f32_32x32x16_bf16 v[18:33], v[136:139], v[66:69], v[18:33]
	v_mfma_f32_32x32x16_bf16 v[2:17], v[70:73], v[66:69], v[2:17]
	v_cvt_pk_bf16_f32 v66, v75, v76
	v_cvt_pk_bf16_f32 v67, v77, v78
	v_cvt_pk_bf16_f32 v68, v79, v80
	v_cvt_pk_bf16_f32 v69, v81, v82
	s_waitcnt lgkmcnt(0)
	s_nop 0
	v_mfma_f32_32x32x16_bf16 v[50:65], v[96:99], v[66:69], v[50:65]
	v_mfma_f32_32x32x16_bf16 v[34:49], v[92:95], v[66:69], v[34:49]
	v_mfma_f32_32x32x16_bf16 v[18:33], v[88:91], v[66:69], v[18:33]
	v_mfma_f32_32x32x16_bf16 v[2:17], v[84:87], v[66:69], v[2:17]
	v_mov_b32_e32 v66, v74
	s_mov_b64 s[52:53], -1
	s_and_b64 vcc, exec, s[44:45]
	s_cbranch_vccnz .LBB0_524
	s_branch .LBB0_525

; __device__ __forceinline__ unsigned pk2(float lo, float hi) { return pg8::cvt_pk_bf16(lo, hi); }
; #define FA_MFMA(a, b, c) __builtin_amdgcn_mfma_f32_32x32x16_bf16((a), (b), (c), 0, 0, 0)
; template <int DQK, bool HAS_LSE>
; __device__ __forceinline__ void unit(LAS unsigned char* lds, const Desc& d) {
;     ...
;             float ls = 0.f;
; #pragma unroll
;             for (int i = 0; i < 16; ++i) { p0[i] = __builtin_amdgcn_exp2f(p0[i] - mn); p1[i] = __builtin_amdgcn_exp2f(p1[i] - mn); ls += p0[i] + p1[i]; }
;             l = l * corr + ls;
;             if (grew) {
; #pragma unroll
;                 for (int db = 0; db < 4; ++db)
; #pragma unroll
;                     for (int i = 0; i < 16; ++i) o[db][i] *= corr;
;             }
; #pragma unroll
;             for (int g4 = 0; g4 < 4; ++g4) {
;                 v4u pkw;
;                 if (g4 == 0) { pkw.x = pk2(p0[0], p0[1]); pkw.y = pk2(p0[2], p0[3]); pkw.z = pk2(p0[4], p0[5]); pkw.w = pk2(p0[6], p0[7]); }
;                 if (g4 == 1) { pkw.x = pk2(p0[8], p0[9]); pkw.y = pk2(p0[10], p0[11]); pkw.z = pk2(p0[12], p0[13]); pkw.w = pk2(p0[14], p0[15]); }
;                 if (g4 == 2) { pkw.x = pk2(p1[0], p1[1]); pkw.y = pk2(p1[2], p1[3]); pkw.z = pk2(p1[4], p1[5]); pkw.w = pk2(p1[6], p1[7]); }
;                 if (g4 == 3) { pkw.x = pk2(p1[8], p1[9]); pkw.y = pk2(p1[10], p1[11]); pkw.z = pk2(p1[12], p1[13]); pkw.w = pk2(p1[14], p1[15]); }
;                 const bf16x8 pf = __builtin_bit_cast(bf16x8, pkw);
;                 vtr8_wait(vlo[g4 & 1], vhh[g4 & 1]);
;                 if (g4 == 0) vtr8_issue<4096>(vba, vlo[1], vhh[1]);
;                 if (g4 == 1) vtr8_issue<8192>(vba, vlo[0], vhh[0]);
;                 if (g4 == 2) vtr8_issue<12288>(vba, vlo[1], vhh[1]);
; #pragma unroll
;                 for (int db = 0; db < 4; ++db) {
;                     const bf16x8 vf = __builtin_shufflevector(vlo[g4 & 1][db], vhh[g4 & 1][db], 0, 1, 2, 3, 4, 5, 6, 7);
;                     o[db] = FA_MFMA(vf, pf, o[db]);
;                 }
;             }
.LBB0_1999:
	v_sub_f32_e32 v82, v82, v186
	v_sub_f32_e32 v66, v66, v186
	v_exp_f32_e32 v189, v82
	v_exp_f32_e32 v82, v66
	v_sub_f32_e32 v83, v83, v186
	v_sub_f32_e32 v67, v67, v186
	v_exp_f32_e32 v190, v83
	v_exp_f32_e32 v83, v67
	v_add_f32_e32 v66, v189, v82
	v_sub_f32_e32 v68, v68, v186
	v_add_f32_e32 v67, v190, v83
	v_add_f32_e32 v66, v67, v66
	v_sub_f32_e32 v67, v84, v186
	v_exp_f32_e32 v67, v67
	v_exp_f32_e32 v188, v68
	v_sub_f32_e32 v69, v69, v186
	v_sub_f32_e32 v70, v70, v186
	v_add_f32_e32 v68, v67, v188
	v_add_f32_e32 v66, v68, v66
	v_sub_f32_e32 v68, v85, v186
	v_exp_f32_e32 v68, v68
	v_exp_f32_e32 v85, v69
	s_nop 0
	v_add_f32_e32 v69, v68, v85
	v_add_f32_e32 v66, v69, v66
	v_sub_f32_e32 v69, v86, v186
	v_exp_f32_e32 v69, v69
	v_exp_f32_e32 v86, v70
	s_nop 0
	v_add_f32_e32 v70, v69, v86
	v_add_f32_e32 v66, v70, v66
	v_sub_f32_e32 v70, v87, v186
	v_exp_f32_e32 v191, v70
	v_sub_f32_e32 v70, v71, v186
	v_exp_f32_e32 v87, v70
	s_nop 0
	v_add_f32_e32 v70, v191, v87
	v_add_f32_e32 v66, v70, v66
	v_sub_f32_e32 v70, v88, v186
	v_exp_f32_e32 v192, v70
	v_sub_f32_e32 v70, v72, v186
	v_exp_f32_e32 v88, v70
	s_nop 0
	v_add_f32_e32 v70, v192, v88
	v_add_f32_e32 v66, v70, v66
	v_sub_f32_e32 v70, v89, v186
	v_exp_f32_e32 v193, v70
	v_sub_f32_e32 v70, v73, v186
	v_exp_f32_e32 v89, v70
	s_nop 0
	v_add_f32_e32 v70, v193, v89
	v_add_f32_e32 v66, v70, v66
	v_sub_f32_e32 v70, v90, v186
	v_exp_f32_e32 v194, v70
	v_sub_f32_e32 v70, v74, v186
	v_exp_f32_e32 v84, v70
	s_nop 0
	v_add_f32_e32 v70, v194, v84
	v_add_f32_e32 v66, v70, v66
	v_sub_f32_e32 v70, v91, v186
	v_exp_f32_e32 v195, v70
	v_sub_f32_e32 v70, v75, v186
	v_exp_f32_e32 v75, v70
	s_nop 0
	v_add_f32_e32 v70, v195, v75
	v_add_f32_e32 v66, v70, v66
	v_sub_f32_e32 v70, v92, v186
	v_exp_f32_e32 v196, v70
	v_sub_f32_e32 v70, v76, v186
	v_exp_f32_e32 v76, v70
	s_nop 0
	v_add_f32_e32 v70, v196, v76
	v_add_f32_e32 v66, v70, v66
	v_sub_f32_e32 v70, v93, v186
	v_exp_f32_e32 v197, v70
	v_sub_f32_e32 v70, v77, v186
	v_exp_f32_e32 v77, v70
	s_nop 0
	v_add_f32_e32 v70, v197, v77
	v_add_f32_e32 v66, v70, v66
	v_sub_f32_e32 v70, v94, v186
	v_exp_f32_e32 v198, v70
	v_sub_f32_e32 v70, v78, v186
	v_exp_f32_e32 v78, v70
	s_nop 0
	v_add_f32_e32 v70, v198, v78
	v_add_f32_e32 v66, v70, v66
	v_sub_f32_e32 v70, v95, v186
	v_exp_f32_e32 v199, v70
	v_sub_f32_e32 v70, v79, v186
	v_exp_f32_e32 v79, v70
	s_nop 0
	v_add_f32_e32 v70, v199, v79
	v_add_f32_e32 v66, v70, v66
	v_sub_f32_e32 v70, v96, v186
	v_exp_f32_e32 v200, v70
	v_sub_f32_e32 v70, v80, v186
	v_exp_f32_e32 v80, v70
	s_nop 0
	v_add_f32_e32 v70, v200, v80
	v_add_f32_e32 v66, v70, v66
	v_sub_f32_e32 v70, v97, v186
	v_exp_f32_e32 v201, v70
	v_sub_f32_e32 v70, v81, v186
	v_exp_f32_e32 v81, v70
	s_nop 0
	v_add_f32_e32 v70, v201, v81
	v_add_f32_e32 v74, v70, v66
	v_cvt_pk_bf16_f32 v70, v189, v190
	v_cvt_pk_bf16_f32 v71, v67, v68
	v_cvt_pk_bf16_f32 v72, v69, v191
	v_cvt_pk_bf16_f32 v73, v192, v193
	s_waitcnt lgkmcnt(0)
	ds_read_b64_tr_b16 v[190:191], v185 offset:4096
	ds_read_b64_tr_b16 v[192:193], v185 offset:6144
	ds_read_b64_tr_b16 v[94:95], v185 offset:4608
	ds_read_b64_tr_b16 v[96:97], v185 offset:6656
	ds_read_b64_tr_b16 v[90:91], v185 offset:5120
	ds_read_b64_tr_b16 v[92:93], v185 offset:7168
	ds_read_b64_tr_b16 v[66:67], v185 offset:5632
	ds_read_b64_tr_b16 v[68:69], v185 offset:7680
	v_fmac_f32_e32 v74, v187, v0
	v_mfma_f32_32x32x16_bf16 v[50:65], v[158:161], v[70:73], v[50:65]
	v_mov_b32_e32 v187, v74
	v_mfma_f32_32x32x16_bf16 v[34:49], v[154:157], v[70:73], v[34:49]
	v_mfma_f32_32x32x16_bf16 v[18:33], v[150:153], v[70:73], v[18:33]
	v_mfma_f32_32x32x16_bf16 v[2:17], v[146:149], v[70:73], v[2:17]
	v_cvt_pk_bf16_f32 v146, v194, v195
	v_cvt_pk_bf16_f32 v147, v196, v197
	v_cvt_pk_bf16_f32 v148, v198, v199
	v_cvt_pk_bf16_f32 v149, v200, v201
	s_waitcnt lgkmcnt(0)
	ds_read_b64_tr_b16 v[158:159], v185 offset:8192
	ds_read_b64_tr_b16 v[160:161], v185 offset:10240
	ds_read_b64_tr_b16 v[154:155], v185 offset:8704
	ds_read_b64_tr_b16 v[156:157], v185 offset:10752
	ds_read_b64_tr_b16 v[150:151], v185 offset:9216
	ds_read_b64_tr_b16 v[152:153], v185 offset:11264
	ds_read_b64_tr_b16 v[70:71], v185 offset:9728
	ds_read_b64_tr_b16 v[72:73], v185 offset:11776
	s_nop 0
	v_mfma_f32_32x32x16_bf16 v[50:65], v[190:193], v[146:149], v[50:65]
	v_mfma_f32_32x32x16_bf16 v[34:49], v[94:97], v[146:149], v[34:49]
	v_mfma_f32_32x32x16_bf16 v[18:33], v[90:93], v[146:149], v[18:33]
	v_mfma_f32_32x32x16_bf16 v[2:17], v[66:69], v[146:149], v[2:17]
	v_cvt_pk_bf16_f32 v66, v82, v83
	v_cvt_pk_bf16_f32 v67, v188, v85
	v_cvt_pk_bf16_f32 v68, v86, v87
	v_cvt_pk_bf16_f32 v69, v88, v89
	s_waitcnt lgkmcnt(0)
	ds_read_b64_tr_b16 v[146:147], v185 offset:12288
	ds_read_b64_tr_b16 v[148:149], v185 offset:14336
	ds_read_b64_tr_b16 v[94:95], v185 offset:12800
	ds_read_b64_tr_b16 v[96:97], v185 offset:14848
	ds_read_b64_tr_b16 v[90:91], v185 offset:13312
	ds_read_b64_tr_b16 v[92:93], v185 offset:15360
	ds_read_b64_tr_b16 v[86:87], v185 offset:13824
	ds_read_b64_tr_b16 v[88:89], v185 offset:15872
	s_nop 0
	v_mfma_f32_32x32x16_bf16 v[50:65], v[158:161], v[66:69], v[50:65]
	v_mfma_f32_32x32x16_bf16 v[34:49], v[154:157], v[66:69], v[34:49]
	v_mfma_f32_32x32x16_bf16 v[18:33], v[150:153], v[66:69], v[18:33]
	v_mfma_f32_32x32x16_bf16 v[2:17], v[70:73], v[66:69], v[2:17]
	v_cvt_pk_bf16_f32 v66, v84, v75
	v_cvt_pk_bf16_f32 v67, v76, v77
	v_cvt_pk_bf16_f32 v68, v78, v79
	v_cvt_pk_bf16_f32 v69, v80, v81
	s_waitcnt lgkmcnt(0)
	s_nop 0
	v_mfma_f32_32x32x16_bf16 v[50:65], v[146:149], v[66:69], v[50:65]
	v_mfma_f32_32x32x16_bf16 v[34:49], v[94:97], v[66:69], v[34:49]
	v_mfma_f32_32x32x16_bf16 v[18:33], v[90:93], v[66:69], v[18:33]
	v_mfma_f32_32x32x16_bf16 v[2:17], v[86:89], v[66:69], v[2:17]
	s_mov_b64 s[42:43], -1
	s_and_b64 vcc, exec, s[8:9]
	s_cbranch_vccnz .LBB0_2001
	s_branch .LBB0_2002
